# attention QK sections: first 20 finishSM VALU ops issued under the LDS latency of the first K-fragment reads (before the first QK MFMA), rest spread over MFMA gaps 1..15
# speedup vs baseline: 1.0126x; 1.0001x over previous
; __device__ __forceinline__ void finishSM(f32x16& p0, f32x16& p1, float alpha, float& l_reg, bf16x8& pa0, bf16x8& pa1, bf16x8& pa2, bf16x8& pa3) {
;     for (int r = 0; r < 16; ++r) p1[r] = __builtin_amdgcn_exp2f(p1[r]);
;     float ps = 0; for (int r = 0; r < 16; ++r) ps += p0[r]; for (int r = 0; r < 16; ++r) ps += p1[r];
;     { auto rr = __builtin_amdgcn_permlane32_swap(__float_as_uint(ps), __float_as_uint(ps), false, false);
;       ps = __uint_as_float(rr[0]) + __uint_as_float(rr[1]); }
;     l_reg = l_reg * alpha + ps;
;     ...
;     PK4(p0, 0, pa0); PK4(p0, 8, pa1); PK4(p1, 0, pa2); PK4(p1, 8, pa3);
;     ...
; }
; template <int KB>
; __device__ __forceinline__ void qkt(f32x16& p0, f32x16& p1, const char* K_lds, int r32, int hi, const bf16x8* qr) {
;     p0 = f32x16{}; p1 = f32x16{};
;     const char* kb[4];
; #pragma unroll
;     for (int dd = 0; dd < 4; ++dd) kb[dd] = K_lds + KB * SHM_K + KSWZ(r32, (dd * 16 + hi * 8) * 2);
; #pragma unroll
;     for (int d0 = 0; d0 < 8; ++d0) { const char* a = kb[d0 & 3] + (d0 >> 2) * 128;
;         bf16x8 b0 = *reinterpret_cast<const bf16x8*>(a);
;         bf16x8 b1 = *reinterpret_cast<const bf16x8*>(a + 32 * 256);
;         p0 = __builtin_amdgcn_mfma_f32_32x32x16_bf16(b0, qr[d0], p0, 0, 0, 0);
;         p1 = __builtin_amdgcn_mfma_f32_32x32x16_bf16(b1, qr[d0], p1, 0, 0, 0); }
; }
.Lmy_hs1_nov:
	s_mov_b32 s100, 0
	ds_read_b128 v[66:69], v169 offset:49152
	ds_read_b128 v[70:73], v169 offset:57344
	ds_read_b128 v[100:103], v193 offset:49152
	ds_read_b128 v[136:139], v193 offset:57344
	v_add_f32_e32 v148, 0, v231
	v_add_f32_e32 v148, v233, v148
	v_add_f32_e32 v148, v229, v148
	v_add_f32_e32 v148, v232, v148
	v_add_f32_e32 v148, v228, v148
	v_add_f32_e32 v148, v230, v148
	v_add_f32_e32 v148, v226, v148
	v_add_f32_e32 v148, v227, v148
	v_add_f32_e32 v148, v223, v148
	v_add_f32_e32 v148, v225, v148
	v_add_f32_e32 v148, v209, v148
	v_add_f32_e32 v148, v224, v148
	v_add_f32_e32 v148, v206, v148
	v_add_f32_e32 v148, v208, v148
	v_add_f32_e32 v148, v205, v148
	v_add_f32_e32 v148, v207, v148
	v_exp_f32_e32 v140, v152
	v_exp_f32_e32 v141, v153
	v_exp_f32_e32 v142, v180
	v_exp_f32_e32 v143, v181
	s_waitcnt lgkmcnt(3)
	v_mfma_f32_32x32x16_bf16 v[82:97], v[66:69], v[132:135], 0
	v_exp_f32_e32 v144, v160
	v_exp_f32_e32 v145, v161
	v_exp_f32_e32 v146, v154
	v_exp_f32_e32 v147, v155
	s_waitcnt lgkmcnt(2)
	v_mfma_f32_32x32x16_bf16 v[66:81], v[70:73], v[132:135], 0
	v_exp_f32_e32 v178, v178
	v_exp_f32_e32 v179, v179
	v_exp_f32_e32 v162, v162
	v_exp_f32_e32 v163, v163
	s_waitcnt lgkmcnt(1)
	v_mfma_f32_32x32x16_bf16 v[82:97], v[100:103], v[128:131], v[82:97]
	v_add_f32_e32 v148, v178, v148
	v_add_f32_e32 v148, v179, v148
	v_add_f32_e32 v148, v162, v148
	v_exp_f32_e32 v158, v158
	s_waitcnt lgkmcnt(0)
	v_mfma_f32_32x32x16_bf16 v[66:81], v[136:139], v[128:131], v[66:81]
	v_exp_f32_e32 v159, v159
	v_exp_f32_e32 v156, v156
	v_exp_f32_e32 v157, v157
	v_add_f32_e32 v148, v163, v148
	ds_read_b128 v[100:103], v194 offset:49152
	ds_read_b128 v[136:139], v194 offset:57344
	s_waitcnt lgkmcnt(1)
	v_mfma_f32_32x32x16_bf16 v[82:97], v[100:103], v[124:127], v[82:97]
	v_add_f32_e32 v148, v158, v148
	v_add_f32_e32 v148, v159, v148
	v_add_f32_e32 v148, v156, v148
	v_add_f32_e32 v148, v157, v148
	s_waitcnt lgkmcnt(0)
	v_mfma_f32_32x32x16_bf16 v[66:81], v[136:139], v[124:127], v[66:81]
	v_add_f32_e32 v148, v140, v148
	v_add_f32_e32 v148, v141, v148
	v_add_f32_e32 v148, v142, v148
	v_add_f32_e32 v148, v143, v148
	ds_read_b128 v[100:103], v195 offset:49152
	ds_read_b128 v[136:139], v195 offset:57344
	s_waitcnt lgkmcnt(1)
	v_mfma_f32_32x32x16_bf16 v[82:97], v[100:103], v[120:123], v[82:97]
	v_add_f32_e32 v148, v144, v148
	v_add_f32_e32 v148, v145, v148
	v_add_f32_e32 v148, v146, v148
	v_add_f32_e32 v199, v147, v148
	s_waitcnt lgkmcnt(0)
	v_mfma_f32_32x32x16_bf16 v[66:81], v[136:139], v[120:123], v[66:81]
	v_mov_b32_e32 v200, v199
	s_nop 1
	v_permlane32_swap_b32_e32 v199, v200
	v_cvt_pk_bf16_f32 v148, v231, v233
	v_cvt_pk_bf16_f32 v149, v229, v232
	v_cvt_pk_bf16_f32 v150, v228, v230
	ds_read_b128 v[100:103], v169 offset:49280
	ds_read_b128 v[136:139], v169 offset:57472
	s_waitcnt lgkmcnt(1)
	v_mfma_f32_32x32x16_bf16 v[82:97], v[100:103], v[116:119], v[82:97]
	v_cvt_pk_bf16_f32 v151, v226, v227
	v_cvt_pk_bf16_f32 v152, v223, v225
	v_cvt_pk_bf16_f32 v153, v209, v224
	s_waitcnt lgkmcnt(0)
	v_mfma_f32_32x32x16_bf16 v[66:81], v[136:139], v[116:119], v[66:81]
	v_cvt_pk_bf16_f32 v154, v206, v208
	v_cvt_pk_bf16_f32 v155, v205, v207
	v_cvt_pk_bf16_f32 v158, v158, v159
	ds_read_b128 v[100:103], v193 offset:49280
	ds_read_b128 v[136:139], v193 offset:57472
	s_waitcnt lgkmcnt(1)
	v_mfma_f32_32x32x16_bf16 v[82:97], v[100:103], v[112:115], v[82:97]
	v_cvt_pk_bf16_f32 v159, v156, v157
	v_cvt_pk_bf16_f32 v156, v178, v179
	v_cvt_pk_bf16_f32 v157, v162, v163
	s_waitcnt lgkmcnt(0)
	v_mfma_f32_32x32x16_bf16 v[66:81], v[136:139], v[112:115], v[66:81]
	v_cvt_pk_bf16_f32 v160, v140, v141
	v_cvt_pk_bf16_f32 v161, v142, v143
	v_cvt_pk_bf16_f32 v162, v144, v145
	ds_read_b128 v[100:103], v194 offset:49280
	ds_read_b128 v[136:139], v194 offset:57472
	s_waitcnt lgkmcnt(1)
	v_mfma_f32_32x32x16_bf16 v[82:97], v[100:103], v[108:111], v[82:97]
	v_cvt_pk_bf16_f32 v163, v146, v147
	s_nop 0
	v_permlane32_swap_b32_e32 v148, v150
	v_permlane32_swap_b32_e32 v149, v151
	s_waitcnt lgkmcnt(0)
	v_mfma_f32_32x32x16_bf16 v[66:81], v[136:139], v[108:111], v[66:81]
	v_permlane32_swap_b32_e32 v152, v154
	v_permlane32_swap_b32_e32 v153, v155
	v_permlane32_swap_b32_e32 v156, v158
	ds_read_b128 v[100:103], v195 offset:49280
	ds_read_b128 v[136:139], v195 offset:57472
	ds_read_b64_tr_b16 v[172:173], v185 offset:0
	ds_read_b64_tr_b16 v[174:175], v185 offset:0x800
	ds_read_b64_tr_b16 v[202:203], v185 offset:0x1000
	ds_read_b64_tr_b16 v[204:205], v185 offset:0x1800
	ds_read_b64_tr_b16 v[206:207], v185 offset:0x2000
	ds_read_b64_tr_b16 v[208:209], v185 offset:0x2800
	ds_read_b64_tr_b16 v[224:225], v185 offset:0x3000
	ds_read_b64_tr_b16 v[226:227], v185 offset:0x3800
	s_waitcnt lgkmcnt(9)
	v_mfma_f32_32x32x16_bf16 v[82:97], v[100:103], v[104:107], v[82:97]
	v_permlane32_swap_b32_e32 v157, v159
	v_permlane32_swap_b32_e32 v160, v162
	v_permlane32_swap_b32_e32 v161, v163
	s_waitcnt lgkmcnt(8)
	v_mfma_f32_32x32x16_bf16 v[66:81], v[136:139], v[104:107], v[66:81]
	v_add_u32_e32 v178, s7, v166
	v_add_u32_e32 v100, 1, v178
	v_add_u32_e32 v102, 33, v178
	v_ashrrev_i32_e32 v101, 31, v100
	v_ashrrev_i32_e32 v103, 31, v102
	v_lshlrev_b64 v[140:141], 8, v[100:101]
	v_lshlrev_b64 v[142:143], 8, v[102:103]
	v_lshl_add_u64 v[100:101], v[170:171], 0, v[140:141]
	v_lshl_add_u64 v[136:137], v[170:171], 0, v[142:143]
	v_lshl_add_u64 v[140:141], v[176:177], 0, v[140:141]
	v_lshl_add_u64 v[144:145], v[176:177], 0, v[142:143]
	global_load_dwordx4 v[100:103], v[100:101], off
	s_nop 0
	global_load_dwordx4 v[136:139], v[136:137], off
	s_nop 0
	global_load_dwordx4 v[140:143], v[140:141], off
	s_nop 0
	global_load_dwordx4 v[144:147], v[144:145], off
	s_waitcnt lgkmcnt(0)
; __device__ __forceinline__ void mask_tile(f32x16& p0, f32x16& p1, int dq, unsigned W) {
;     const float NEG = -__builtin_inff();
; #pragma unroll
;     for (int r = 0; r < 16; ++r) {
;         const int c = (r & 3) + 8 * (r >> 2);
;         if ((unsigned)(dq - c) >= W) p0[r] = NEG;
;         if ((unsigned)(dq - c - 32) >= W) p1[r] = NEG;
;     }
; }
; template <int VB>
; __device__ __forceinline__ void pv_tile(f32x16* o, int vb0, bf16x8 pa0, bf16x8 pa1, bf16x8 pa2, bf16x8 pa3) {
;     ...
;     PV_D0(0); PV_D0(1); PV_D0(2); PV_D0(3);
	s_nop 0
	v_mfma_f32_32x32x16_bf16 v[50:65], v[148:151], v[172:175], v[50:65]
	ds_read_b64_tr_b16 v[172:173], v185 offset:0x200
	ds_read_b64_tr_b16 v[174:175], v185 offset:0xa00
	v_mfma_f32_32x32x16_bf16 v[50:65], v[152:155], v[202:205], v[50:65]
	ds_read_b64_tr_b16 v[202:203], v185 offset:0x1200
	ds_read_b64_tr_b16 v[204:205], v185 offset:0x1a00
	v_mfma_f32_32x32x16_bf16 v[50:65], v[156:159], v[206:209], v[50:65]
	ds_read_b64_tr_b16 v[206:207], v185 offset:0x2200
	ds_read_b64_tr_b16 v[208:209], v185 offset:0x2a00
	v_mfma_f32_32x32x16_bf16 v[50:65], v[160:163], v[224:227], v[50:65]
	ds_read_b64_tr_b16 v[224:225], v185 offset:0x3200
	ds_read_b64_tr_b16 v[226:227], v185 offset:0x3a00
	s_waitcnt lgkmcnt(0)
	v_mfma_f32_32x32x16_bf16 v[34:49], v[148:151], v[172:175], v[34:49]
	ds_read_b64_tr_b16 v[172:173], v185 offset:0x400
	ds_read_b64_tr_b16 v[174:175], v185 offset:0xc00
	v_mfma_f32_32x32x16_bf16 v[34:49], v[152:155], v[202:205], v[34:49]
	ds_read_b64_tr_b16 v[202:203], v185 offset:0x1400
	ds_read_b64_tr_b16 v[204:205], v185 offset:0x1c00
	v_mfma_f32_32x32x16_bf16 v[34:49], v[156:159], v[206:209], v[34:49]
	ds_read_b64_tr_b16 v[206:207], v185 offset:0x2400
	ds_read_b64_tr_b16 v[208:209], v185 offset:0x2c00
	v_mfma_f32_32x32x16_bf16 v[34:49], v[160:163], v[224:227], v[34:49]
	ds_read_b64_tr_b16 v[224:225], v185 offset:0x3400
	ds_read_b64_tr_b16 v[226:227], v185 offset:0x3c00
	s_waitcnt lgkmcnt(0)
	v_mfma_f32_32x32x16_bf16 v[18:33], v[148:151], v[172:175], v[18:33]
	ds_read_b64_tr_b16 v[172:173], v185 offset:0x600
	ds_read_b64_tr_b16 v[174:175], v185 offset:0xe00
	v_mfma_f32_32x32x16_bf16 v[18:33], v[152:155], v[202:205], v[18:33]
	ds_read_b64_tr_b16 v[202:203], v185 offset:0x1600
	ds_read_b64_tr_b16 v[204:205], v185 offset:0x1e00
	v_mfma_f32_32x32x16_bf16 v[18:33], v[156:159], v[206:209], v[18:33]
	ds_read_b64_tr_b16 v[206:207], v185 offset:0x2600
	ds_read_b64_tr_b16 v[208:209], v185 offset:0x2e00
	v_mfma_f32_32x32x16_bf16 v[18:33], v[160:163], v[224:227], v[18:33]
	ds_read_b64_tr_b16 v[224:225], v185 offset:0x3600
	ds_read_b64_tr_b16 v[226:227], v185 offset:0x3e00
	s_waitcnt lgkmcnt(0)
	v_mfma_f32_32x32x16_bf16 v[2:17], v[148:151], v[172:175], v[2:17]
	s_cmp_le_i32 s7, s6
	v_mfma_f32_32x32x16_bf16 v[2:17], v[152:155], v[202:205], v[2:17]
	v_mfma_f32_32x32x16_bf16 v[2:17], v[156:159], v[206:209], v[2:17]
	v_mfma_f32_32x32x16_bf16 v[2:17], v[160:163], v[224:227], v[2:17]
	s_cbranch_scc1 .LBB0_91
	v_add_u32_e32 v148, 0x4000007b, v197
	v_cmp_gt_u32_e32 vcc, 2.0, v148
	v_add_u32_e32 v148, 0x5b, v197
	s_nop 0
	v_cndmask_b32_e32 v82, v220, v82, vcc
	v_cmp_lt_u32_e32 vcc, s33, v148
	v_add_u32_e32 v148, 0x7a, v197
	s_nop 0
	v_cndmask_b32_e32 v66, v220, v66, vcc
	v_cmp_lt_u32_e32 vcc, s33, v148
	v_add_u32_e32 v148, 0x5a, v197
	s_nop 0
	v_cndmask_b32_e32 v83, v220, v83, vcc
	v_cmp_lt_u32_e32 vcc, s33, v148
	v_add_u32_e32 v148, 0x79, v197
	s_nop 0
	v_cndmask_b32_e32 v67, v220, v67, vcc
	v_cmp_lt_u32_e32 vcc, s33, v148
	v_add_u32_e32 v148, 0x59, v197
	s_nop 0
	v_cndmask_b32_e32 v84, v220, v84, vcc
	v_cmp_lt_u32_e32 vcc, s33, v148
	v_add_u32_e32 v148, 0x78, v197
	s_nop 0
	v_cndmask_b32_e32 v68, v220, v68, vcc
	v_cmp_lt_u32_e32 vcc, s33, v148
	v_add_u32_e32 v148, 0x58, v197
	s_nop 0
	v_cndmask_b32_e32 v85, v220, v85, vcc
	v_cmp_lt_u32_e32 vcc, s33, v148
	v_add_u32_e32 v148, 0x73, v197
	s_nop 0
	v_cndmask_b32_e32 v69, v220, v69, vcc
	v_cmp_lt_u32_e32 vcc, s33, v148
	v_add_u32_e32 v148, 0x53, v197
	s_nop 0
	v_cndmask_b32_e32 v86, v220, v86, vcc
	v_cmp_lt_u32_e32 vcc, s33, v148
	v_add_u32_e32 v148, 0x72, v197
	s_nop 0
	v_cndmask_b32_e32 v70, v220, v70, vcc
	v_cmp_lt_u32_e32 vcc, s33, v148
	v_add_u32_e32 v148, 0x52, v197
	s_nop 0
	v_cndmask_b32_e32 v87, v220, v87, vcc
	v_cmp_lt_u32_e32 vcc, s33, v148
	v_add_u32_e32 v148, 0x71, v197
	s_nop 0
	v_cndmask_b32_e32 v71, v220, v71, vcc
	v_cmp_lt_u32_e32 vcc, s33, v148
	v_add_u32_e32 v148, 0x51, v197
	s_nop 0
	v_cndmask_b32_e32 v88, v220, v88, vcc
	v_cmp_lt_u32_e32 vcc, s33, v148
	v_add_u32_e32 v148, 0x70, v197
	s_nop 0
	v_cndmask_b32_e32 v72, v220, v72, vcc
	v_cmp_lt_u32_e32 vcc, s33, v148
	v_add_u32_e32 v148, 0x50, v197
	s_nop 0
	v_cndmask_b32_e32 v89, v220, v89, vcc
	v_cmp_lt_u32_e32 vcc, s33, v148
	v_add_u32_e32 v148, 0x6b, v197
	s_nop 0
	v_cndmask_b32_e32 v73, v220, v73, vcc
	v_cmp_lt_u32_e32 vcc, s33, v148
	v_add_u32_e32 v148, 0x4b, v197
	s_nop 0
	v_cndmask_b32_e32 v90, v220, v90, vcc
	v_cmp_lt_u32_e32 vcc, s33, v148
	v_add_u32_e32 v148, 0x6a, v197
	s_nop 0
	v_cndmask_b32_e32 v74, v220, v74, vcc
	v_cmp_lt_u32_e32 vcc, s33, v148
	v_add_u32_e32 v148, 0x4a, v197
	s_nop 0
	v_cndmask_b32_e32 v91, v220, v91, vcc
	v_cmp_lt_u32_e32 vcc, s33, v148
	v_add_u32_e32 v148, 0x69, v197
	s_nop 0
	v_cndmask_b32_e32 v75, v220, v75, vcc
	v_cmp_lt_u32_e32 vcc, s33, v148
	v_add_u32_e32 v148, 0x49, v197
	s_nop 0
	v_cndmask_b32_e32 v92, v220, v92, vcc
	v_cmp_lt_u32_e32 vcc, s33, v148
	v_add_u32_e32 v148, 0x68, v197
	s_nop 0
	v_cndmask_b32_e32 v76, v220, v76, vcc
	v_cmp_lt_u32_e32 vcc, s33, v148
	v_add_u32_e32 v148, 0x48, v197
	s_nop 0
	v_cndmask_b32_e32 v93, v220, v93, vcc
	v_cmp_lt_u32_e32 vcc, s33, v148
	v_add_u32_e32 v148, 0x63, v197
	s_nop 0
	v_cndmask_b32_e32 v77, v220, v77, vcc
	v_cmp_lt_u32_e32 vcc, s33, v148
	v_add_u32_e32 v148, 0x43, v197
	s_nop 0
	v_cndmask_b32_e32 v94, v220, v94, vcc
	v_cmp_lt_u32_e32 vcc, s33, v148
	v_add_u32_e32 v148, 0x62, v197
	s_nop 0
	v_cndmask_b32_e32 v78, v220, v78, vcc
	v_cmp_lt_u32_e32 vcc, s33, v148
	v_add_u32_e32 v148, 0x42, v197
	s_nop 0
	v_cndmask_b32_e32 v95, v220, v95, vcc
	v_cmp_lt_u32_e32 vcc, s33, v148
	v_add_u32_e32 v148, 0x61, v197
	s_nop 0
	v_cndmask_b32_e32 v79, v220, v79, vcc
	v_cmp_lt_u32_e32 vcc, s33, v148
	v_add_u32_e32 v148, 0x41, v197
	s_nop 0
	v_cndmask_b32_e32 v96, v220, v96, vcc
	v_cmp_lt_u32_e32 vcc, s33, v148
	v_add_u32_e32 v148, 0x60, v197
	s_nop 0
	v_cndmask_b32_e32 v80, v220, v80, vcc
	v_cmp_lt_u32_e32 vcc, s33, v148
	v_add_u32_e32 v148, 64, v197
	s_nop 0
	v_cndmask_b32_e32 v97, v220, v97, vcc
	v_cmp_lt_u32_e32 vcc, s33, v148
	s_nop 1
	v_cndmask_b32_e32 v81, v220, v81, vcc

; __device__ __forceinline__ void partialSM(f32x16& p0, f32x16& p1, float& m_reg, float& mn, float& alpha, bool rs) {
;     ...
;     constexpr float C2 = 1.4426950408889634f * SCALE;
;     if (__builtin_expect(__all((pmax - m_reg) * SCALE <= THR), 1)) { mn = m_reg; alpha = 1.f; }
;     else { mn = fmaxf(m_reg, pmax); alpha = __builtin_amdgcn_exp2f((m_reg - mn) * C2); m_reg = mn; }
;     const float mnL = rs ? -mn * C2 : -__builtin_inff();
;     for (int r = 0; r < 16; ++r) p0[r] = fmaf(p0[r], C2, mnL); for (int r = 0; r < 16; ++r) p1[r] = fmaf(p1[r], C2, mnL);
;     for (int r = 0; r < 16; ++r) p0[r] = __builtin_amdgcn_exp2f(p0[r]);
.LBB0_95:
	v_cndmask_b32_e64 v179, v148, v198, s[42:43]
	v_mul_f32_e32 v148, 0xbe0293ee, v179
	v_cndmask_b32_e64 v180, v220, v148, s[40:41]
	v_fmamk_f32 v82, v82, 0x3e0293ee, v180
	v_fmamk_f32 v83, v83, 0x3e0293ee, v180
	v_fmamk_f32 v84, v84, 0x3e0293ee, v180
	v_fmamk_f32 v85, v85, 0x3e0293ee, v180
	v_fmamk_f32 v86, v86, 0x3e0293ee, v180
	v_fmamk_f32 v87, v87, 0x3e0293ee, v180
	v_fmamk_f32 v88, v88, 0x3e0293ee, v180
	v_fmamk_f32 v89, v89, 0x3e0293ee, v180
	v_fmamk_f32 v90, v90, 0x3e0293ee, v180
	v_fmamk_f32 v91, v91, 0x3e0293ee, v180
	v_fmamk_f32 v92, v92, 0x3e0293ee, v180
	v_fmamk_f32 v93, v93, 0x3e0293ee, v180
	v_fmamk_f32 v94, v94, 0x3e0293ee, v180
	v_fmamk_f32 v95, v95, 0x3e0293ee, v180
	v_fmamk_f32 v96, v96, 0x3e0293ee, v180
	v_fmamk_f32 v97, v97, 0x3e0293ee, v180
	v_exp_f32_e32 v148, v82
	v_exp_f32_e32 v163, v83
	v_exp_f32_e32 v149, v84
	v_exp_f32_e32 v162, v85
	v_exp_f32_e32 v150, v86
	v_exp_f32_e32 v161, v87
	v_exp_f32_e32 v151, v88
	v_exp_f32_e32 v160, v89
	v_exp_f32_e32 v152, v90
	v_exp_f32_e32 v159, v91
	v_exp_f32_e32 v153, v92
	v_exp_f32_e32 v158, v93
	v_exp_f32_e32 v154, v94
	v_exp_f32_e32 v157, v95
	v_exp_f32_e32 v155, v96
	v_exp_f32_e32 v156, v97
	v_fmamk_f32 v203, v73, 0x3e0293ee, v180
	v_fmamk_f32 v204, v74, 0x3e0293ee, v180
	v_fmamk_f32 v208, v66, 0x3e0293ee, v180
	v_fmamk_f32 v209, v67, 0x3e0293ee, v180
	v_fmamk_f32 v223, v68, 0x3e0293ee, v180
	v_fmamk_f32 v224, v69, 0x3e0293ee, v180
	v_fmamk_f32 v225, v70, 0x3e0293ee, v180
	v_fmamk_f32 v198, v71, 0x3e0293ee, v180
	v_fmamk_f32 v201, v72, 0x3e0293ee, v180
	v_fmamk_f32 v205, v75, 0x3e0293ee, v180
	v_fmamk_f32 v206, v76, 0x3e0293ee, v180
	v_fmamk_f32 v207, v77, 0x3e0293ee, v180
	v_fmamk_f32 v181, v78, 0x3e0293ee, v180
	v_fmamk_f32 v226, v79, 0x3e0293ee, v180
	v_fmamk_f32 v227, v80, 0x3e0293ee, v180
	v_fmac_f32_e32 v180, 0x3e0293ee, v81
	s_waitcnt lgkmcnt(0)
	s_barrier
; __device__ __forceinline__ void finishSM(f32x16& p0, f32x16& p1, float alpha, float& l_reg, bf16x8& pa0, bf16x8& pa1, bf16x8& pa2, bf16x8& pa3) {
;     for (int r = 0; r < 16; ++r) p1[r] = __builtin_amdgcn_exp2f(p1[r]);
;     float ps = 0; for (int r = 0; r < 16; ++r) ps += p0[r]; for (int r = 0; r < 16; ++r) ps += p1[r];
;     { auto rr = __builtin_amdgcn_permlane32_swap(__float_as_uint(ps), __float_as_uint(ps), false, false);
;       ps = __uint_as_float(rr[0]) + __uint_as_float(rr[1]); }
;     l_reg = l_reg * alpha + ps;
;     ...
;     PK4(p0, 0, pa0); PK4(p0, 8, pa1); PK4(p1, 0, pa2); PK4(p1, 8, pa3);
;     ...
; }
; template <int KB>
; __device__ __forceinline__ void qkt(f32x16& p0, f32x16& p1, const char* K_lds, int r32, int hi, const bf16x8* qr) {
;     p0 = f32x16{}; p1 = f32x16{};
;     const char* kb[4];
; #pragma unroll
;     for (int dd = 0; dd < 4; ++dd) kb[dd] = K_lds + KB * SHM_K + KSWZ(r32, (dd * 16 + hi * 8) * 2);
; #pragma unroll
;     for (int d0 = 0; d0 < 8; ++d0) { const char* a = kb[d0 & 3] + (d0 >> 2) * 128;
;         bf16x8 b0 = *reinterpret_cast<const bf16x8*>(a);
;         bf16x8 b1 = *reinterpret_cast<const bf16x8*>(a + 32 * 256);
;         p0 = __builtin_amdgcn_mfma_f32_32x32x16_bf16(b0, qr[d0], p0, 0, 0, 0);
;         p1 = __builtin_amdgcn_mfma_f32_32x32x16_bf16(b1, qr[d0], p1, 0, 0, 0); }
; }
	s_waitcnt vmcnt(0)
	ds_write_b128 v191, v[100:103]
	ds_write_b128 v192, v[136:139]
	ds_read_b128 v[66:69], v169 offset:32768
	ds_read_b128 v[70:73], v169 offset:40960
	ds_read_b128 v[172:175], v193 offset:32768
	ds_read_b128 v[228:231], v193 offset:40960
	v_exp_f32_e32 v198, v198
	v_exp_f32_e32 v201, v201
	v_exp_f32_e32 v214, v204
	v_exp_f32_e32 v205, v205
	v_exp_f32_e32 v206, v206
	v_exp_f32_e32 v207, v207
	v_exp_f32_e32 v181, v181
	v_exp_f32_e32 v215, v226
	v_exp_f32_e32 v216, v227
	v_exp_f32_e32 v180, v180
	v_exp_f32_e32 v218, v209
	v_exp_f32_e32 v209, v203
	v_add_f32_e32 v203, 0, v148
	v_add_f32_e32 v203, v163, v203
	v_add_f32_e32 v203, v149, v203
	v_add_f32_e32 v203, v162, v203
	v_add_f32_e32 v203, v150, v203
	v_add_f32_e32 v203, v161, v203
	v_add_f32_e32 v203, v151, v203
	v_add_f32_e32 v203, v160, v203
	s_waitcnt lgkmcnt(3)
	v_mfma_f32_32x32x16_bf16 v[82:97], v[66:69], v[132:135], 0
	v_add_f32_e32 v203, v152, v203
	v_add_f32_e32 v203, v159, v203
	v_add_f32_e32 v203, v153, v203
	v_add_f32_e32 v203, v158, v203
	s_waitcnt lgkmcnt(2)
	v_mfma_f32_32x32x16_bf16 v[66:81], v[70:73], v[132:135], 0
	v_exp_f32_e32 v217, v208
	v_add_f32_e32 v203, v154, v203
	v_add_f32_e32 v203, v157, v203
	v_exp_f32_e32 v219, v223
	s_waitcnt lgkmcnt(1)
	v_mfma_f32_32x32x16_bf16 v[82:97], v[172:175], v[128:131], v[82:97]
	v_add_f32_e32 v203, v155, v203
	v_exp_f32_e32 v222, v224
	v_add_f32_e32 v203, v156, v203
	v_exp_f32_e32 v208, v225
	s_waitcnt lgkmcnt(0)
	v_mfma_f32_32x32x16_bf16 v[66:81], v[228:231], v[128:131], v[66:81]
	v_add_f32_e32 v203, v217, v203
	v_add_f32_e32 v203, v218, v203
	v_add_f32_e32 v203, v219, v203
	v_add_f32_e32 v203, v222, v203
	ds_read_b128 v[172:175], v194 offset:32768
	ds_read_b128 v[228:231], v194 offset:40960
	s_waitcnt lgkmcnt(1)
	v_mfma_f32_32x32x16_bf16 v[82:97], v[172:175], v[124:127], v[82:97]
	v_add_f32_e32 v203, v208, v203
	v_add_f32_e32 v203, v198, v203
	v_add_f32_e32 v203, v201, v203
	v_add_f32_e32 v203, v209, v203
	s_waitcnt lgkmcnt(0)
	v_mfma_f32_32x32x16_bf16 v[66:81], v[228:231], v[124:127], v[66:81]
	v_add_f32_e32 v203, v214, v203
	v_add_f32_e32 v203, v205, v203
	v_add_f32_e32 v203, v206, v203
	v_add_f32_e32 v203, v207, v203
	ds_read_b128 v[172:175], v195 offset:32768
	ds_read_b128 v[228:231], v195 offset:40960
	s_waitcnt lgkmcnt(1)
	v_mfma_f32_32x32x16_bf16 v[82:97], v[172:175], v[120:123], v[82:97]
	v_add_f32_e32 v203, v181, v203
	v_add_f32_e32 v203, v215, v203
	v_add_f32_e32 v203, v216, v203
	v_add_f32_e32 v203, v180, v203
	s_waitcnt lgkmcnt(0)
	v_mfma_f32_32x32x16_bf16 v[66:81], v[228:231], v[120:123], v[66:81]
	v_mov_b32_e32 v204, v203
	v_cvt_pk_bf16_f32 v148, v148, v163
	v_cvt_pk_bf16_f32 v149, v149, v162
	v_cvt_pk_bf16_f32 v150, v150, v161
	ds_read_b128 v[172:175], v169 offset:32896
	ds_read_b128 v[228:231], v169 offset:41088
	s_waitcnt lgkmcnt(1)
	v_mfma_f32_32x32x16_bf16 v[82:97], v[172:175], v[116:119], v[82:97]
	v_cvt_pk_bf16_f32 v151, v151, v160
	v_cvt_pk_bf16_f32 v152, v152, v159
	v_cvt_pk_bf16_f32 v153, v153, v158
	v_cvt_pk_bf16_f32 v154, v154, v157
	s_waitcnt lgkmcnt(0)
	v_mfma_f32_32x32x16_bf16 v[66:81], v[228:231], v[116:119], v[66:81]
	v_cvt_pk_bf16_f32 v155, v155, v156
	v_cvt_pk_bf16_f32 v156, v217, v218
	v_cvt_pk_bf16_f32 v157, v219, v222
	ds_read_b128 v[172:175], v193 offset:32896
	ds_read_b128 v[228:231], v193 offset:41088
	s_waitcnt lgkmcnt(1)
	v_mfma_f32_32x32x16_bf16 v[82:97], v[172:175], v[112:115], v[82:97]
	v_cvt_pk_bf16_f32 v158, v208, v198
	v_cvt_pk_bf16_f32 v159, v201, v209
	v_cvt_pk_bf16_f32 v160, v214, v205
	s_waitcnt lgkmcnt(0)
	v_mfma_f32_32x32x16_bf16 v[66:81], v[228:231], v[112:115], v[66:81]
	v_cvt_pk_bf16_f32 v161, v206, v207
	v_cvt_pk_bf16_f32 v162, v181, v215
	v_cvt_pk_bf16_f32 v163, v216, v180
	ds_read_b128 v[172:175], v194 offset:32896
	ds_read_b128 v[228:231], v194 offset:41088
	s_waitcnt lgkmcnt(1)
	v_mfma_f32_32x32x16_bf16 v[82:97], v[172:175], v[108:111], v[82:97]
	s_nop 1
	v_permlane32_swap_b32_e32 v203, v204
	v_permlane32_swap_b32_e32 v148, v150
	v_permlane32_swap_b32_e32 v149, v151
	s_waitcnt lgkmcnt(0)
	v_mfma_f32_32x32x16_bf16 v[66:81], v[228:231], v[108:111], v[66:81]
	v_permlane32_swap_b32_e32 v152, v154
	v_permlane32_swap_b32_e32 v153, v155
	v_permlane32_swap_b32_e32 v156, v158
	ds_read_b128 v[172:175], v195 offset:32896
	ds_read_b128 v[228:231], v195 offset:41088
	ds_read_b64_tr_b16 v[206:207], v185 offset:0x5000
	ds_read_b64_tr_b16 v[208:209], v185 offset:0x5800
	ds_read_b64_tr_b16 v[224:225], v185 offset:0x6000
	ds_read_b64_tr_b16 v[226:227], v185 offset:0x6800
	s_waitcnt lgkmcnt(5)
	v_mfma_f32_32x32x16_bf16 v[82:97], v[172:175], v[104:107], v[82:97]
	v_permlane32_swap_b32_e32 v157, v159
	v_permlane32_swap_b32_e32 v160, v162
	v_permlane32_swap_b32_e32 v161, v163
	s_waitcnt lgkmcnt(4)
	v_mfma_f32_32x32x16_bf16 v[66:81], v[228:231], v[104:107], v[66:81]
	ds_read_b64_tr_b16 v[172:173], v185 offset:0x4000
	ds_read_b64_tr_b16 v[174:175], v185 offset:0x4800
	ds_read_b64_tr_b16 v[228:229], v185 offset:0x7000
	ds_read_b64_tr_b16 v[230:231], v185 offset:0x7800
	s_cmp_lt_u32 s3, s2
	s_cselect_b64 s[22:23], -1, 0
	s_cmp_ge_u32 s3, s2
	s_cbranch_scc1 .LBB0_97
	v_add_u32_e32 v242, 0x41, v178
	v_add_u32_e32 v246, 0x61, v178
	v_ashrrev_i32_e32 v243, 31, v242
	v_ashrrev_i32_e32 v247, 31, v246
	v_lshlrev_b64 v[140:141], 8, v[242:243]
	v_lshlrev_b64 v[142:143], 8, v[246:247]
	v_lshl_add_u64 v[242:243], v[170:171], 0, v[140:141]
	v_lshl_add_u64 v[246:247], v[170:171], 0, v[142:143]
	v_lshl_add_u64 v[140:141], v[176:177], 0, v[140:141]
	v_lshl_add_u64 v[144:145], v[176:177], 0, v[142:143]
	global_load_dwordx4 v[242:245], v[242:243], off
	s_nop 0
	global_load_dwordx4 v[246:249], v[246:247], off
	s_nop 0
	global_load_dwordx4 v[140:143], v[140:141], off
	s_nop 0
	global_load_dwordx4 v[144:147], v[144:145], off
	s_mov_b32 s100, 1
